# hoisted LDS reads in HGRN c3 cumsum loops
# speedup vs baseline: 1.0082x; 1.0031x over previous
; DEV float bf2f(unsigned short b) { return __uint_as_float(((unsigned)b) << 16); }
; DEV void phase_hg_c3(const Params& p, char* smem) {
;     ...
;       } else {
;         float run = half ? 0.f : tot[128 + k];
; #pragma unroll 4
;         for (int s = 31; s >= 0; s--) {
;           const int t = half * 32 + s;
;           const float lf = bf2f(Kin[t * 144 + k]); run += lf;
;           const float q = bf2f(Qin[t * 144 + k]);
;           Qin[t * 144 + k] = f2bf(q * __expf(run));
;           Kin[t * 144 + k] = f2bf((1.f - __expf(lf)) * __expf(-run));
;         }
;       }
.LBB0_285:
	v_add_u32_e32 v108, s6, v147
	ds_read_u16 v109, v108 offset:19296
	ds_read_u16 v110, v108 offset:864
	ds_read_u16 v178, v108 offset:19008
	ds_read_u16 v179, v108 offset:576
	ds_read_u16 v180, v108 offset:18720
	ds_read_u16 v181, v108 offset:288
	ds_read_u16 v182, v108 offset:18432
	ds_read_u16 v183, v108
	s_addk_i32 s6, 0xfb80
	s_cmpk_lg_i32 s6, 0xfb80
	s_waitcnt lgkmcnt(7)
	v_lshlrev_b32_e32 v109, 16, v109
	v_add_f32_e32 v0, v0, v109
	v_mul_f32_e32 v111, 0x3fb8aa3b, v0
	v_exp_f32_e32 v111, v111
	s_waitcnt lgkmcnt(6)
	v_lshlrev_b32_e32 v110, 16, v110
	v_mul_f32_e32 v109, 0x3fb8aa3b, v109
	v_exp_f32_e32 v109, v109
	v_mul_f32_e32 v110, v111, v110
	v_cvt_pk_bf16_f32 v110, v110, s0
	ds_write_b16 v108, v110 offset:864
	v_mul_f32_e32 v110, 0xbfb8aa3b, v0
	v_exp_f32_e32 v110, v110
	v_sub_f32_e32 v109, 1.0, v109
	v_mul_f32_e32 v109, v109, v110
	v_cvt_pk_bf16_f32 v109, v109, s0
	ds_write_b16 v108, v109 offset:19296
	s_waitcnt lgkmcnt(7)
	v_lshlrev_b32_e32 v178, 16, v178
	v_add_f32_e32 v0, v0, v178
	v_mul_f32_e32 v111, 0x3fb8aa3b, v0
	v_exp_f32_e32 v111, v111
	s_waitcnt lgkmcnt(6)
	v_lshlrev_b32_e32 v179, 16, v179
	v_mul_f32_e32 v178, 0x3fb8aa3b, v178
	v_exp_f32_e32 v178, v178
	v_mul_f32_e32 v179, v111, v179
	v_cvt_pk_bf16_f32 v179, v179, s0
	ds_write_b16 v108, v179 offset:576
	v_mul_f32_e32 v179, 0xbfb8aa3b, v0
	v_exp_f32_e32 v179, v179
	v_sub_f32_e32 v178, 1.0, v178
	v_mul_f32_e32 v178, v178, v179
	v_cvt_pk_bf16_f32 v178, v178, s0
	ds_write_b16 v108, v178 offset:19008
	s_waitcnt lgkmcnt(7)
	v_lshlrev_b32_e32 v180, 16, v180
	v_add_f32_e32 v0, v0, v180
	v_mul_f32_e32 v111, 0x3fb8aa3b, v0
	v_exp_f32_e32 v111, v111
	s_waitcnt lgkmcnt(6)
	v_lshlrev_b32_e32 v181, 16, v181
	v_mul_f32_e32 v180, 0x3fb8aa3b, v180
	v_exp_f32_e32 v180, v180
	v_mul_f32_e32 v181, v111, v181
	v_cvt_pk_bf16_f32 v181, v181, s0
	ds_write_b16 v108, v181 offset:288
	v_mul_f32_e32 v181, 0xbfb8aa3b, v0
	v_exp_f32_e32 v181, v181
	v_sub_f32_e32 v180, 1.0, v180
	v_mul_f32_e32 v180, v180, v181
	v_cvt_pk_bf16_f32 v180, v180, s0
	ds_write_b16 v108, v180 offset:18720
	s_waitcnt lgkmcnt(7)
	v_lshlrev_b32_e32 v182, 16, v182
	v_add_f32_e32 v0, v0, v182
	v_mul_f32_e32 v111, 0x3fb8aa3b, v0
	v_exp_f32_e32 v111, v111
	s_waitcnt lgkmcnt(6)
	v_lshlrev_b32_e32 v183, 16, v183
	v_mul_f32_e32 v182, 0x3fb8aa3b, v182
	v_exp_f32_e32 v182, v182
	v_mul_f32_e32 v183, v111, v183
	v_cvt_pk_bf16_f32 v183, v183, s0
	ds_write_b16 v108, v183
	v_mul_f32_e32 v183, 0xbfb8aa3b, v0
	v_exp_f32_e32 v183, v183
	v_sub_f32_e32 v182, 1.0, v182
	v_mul_f32_e32 v182, v182, v183
	v_cvt_pk_bf16_f32 v182, v182, s0
	ds_write_b16 v108, v182 offset:18432
	s_cbranch_scc1 .LBB0_285
	s_mov_b64 s[6:7], 0

; DEV float bf2f(unsigned short b) { return __uint_as_float(((unsigned)b) << 16); }
; DEV void phase_hg_c3(const Params& p, char* smem) {
;     ...
;       if (dir == 0) {
;         float run = half ? tot[k] : 0.f;
; #pragma unroll 4
;         for (int s = 0; s < 32; s++) {
;           const int t = half * 32 + s;
;           const float lf = bf2f(Kin[t * 144 + k]); run += lf;
;           const float q = bf2f(Qin[t * 144 + k]);
;           Qin[t * 144 + k] = f2bf(q * __expf(run));
;           Kin[t * 144 + k] = f2bf((1.f - __expf(lf)) * __expf(-run));
;         }
.LBB0_291:
	v_add_u32_e32 v108, vcc_lo, v147
	ds_read_u16 v109, v108 offset:18432
	ds_read_u16 v110, v108
	ds_read_u16 v178, v108 offset:18720
	ds_read_u16 v179, v108 offset:288
	ds_read_u16 v180, v108 offset:19008
	ds_read_u16 v181, v108 offset:576
	ds_read_u16 v182, v108 offset:19296
	ds_read_u16 v183, v108 offset:864
	s_addk_i32 vcc_lo, 0x480
	s_cmpk_eq_i32 vcc_lo, 0x2400
	s_mov_b64 s[76:77], s[80:81]
	s_waitcnt lgkmcnt(7)
	v_lshlrev_b32_e32 v109, 16, v109
	v_add_f32_e32 v0, v0, v109
	v_mul_f32_e32 v111, 0x3fb8aa3b, v0
	v_exp_f32_e32 v111, v111
	s_waitcnt lgkmcnt(6)
	v_lshlrev_b32_e32 v110, 16, v110
	v_mul_f32_e32 v109, 0x3fb8aa3b, v109
	v_exp_f32_e32 v109, v109
	v_mul_f32_e32 v110, v111, v110
	v_cvt_pk_bf16_f32 v110, v110, s0
	ds_write_b16 v108, v110
	v_mul_f32_e32 v110, 0xbfb8aa3b, v0
	v_exp_f32_e32 v110, v110
	v_sub_f32_e32 v109, 1.0, v109
	s_mov_b64 s[72:73], s[82:83]
	s_mov_b64 s[68:69], s[84:85]
	v_mul_f32_e32 v109, v109, v110
	v_cvt_pk_bf16_f32 v109, v109, s0
	ds_write_b16 v108, v109 offset:18432
	s_mov_b64 s[48:49], s[88:89]
	s_mov_b64 s[64:65], s[30:31]
	s_mov_b64 s[60:61], s[34:35]
	s_waitcnt lgkmcnt(7)
	v_lshlrev_b32_e32 v178, 16, v178
	v_add_f32_e32 v0, v0, v178
	v_mul_f32_e32 v111, 0x3fb8aa3b, v0
	v_exp_f32_e32 v111, v111
	s_waitcnt lgkmcnt(6)
	v_lshlrev_b32_e32 v179, 16, v179
	v_mul_f32_e32 v178, 0x3fb8aa3b, v178
	v_exp_f32_e32 v178, v178
	v_mul_f32_e32 v179, v111, v179
	v_cvt_pk_bf16_f32 v179, v179, s0
	ds_write_b16 v108, v179 offset:288
	v_mul_f32_e32 v179, 0xbfb8aa3b, v0
	v_exp_f32_e32 v179, v179
	v_sub_f32_e32 v178, 1.0, v178
	s_mov_b64 s[56:57], s[86:87]
	s_mov_b64 s[28:29], s[0:1]
	v_mul_f32_e32 v178, v178, v179
	v_cvt_pk_bf16_f32 v178, v178, s0
	ds_write_b16 v108, v178 offset:18720
	s_mov_b64 s[46:47], s[8:9]
	s_mov_b64 s[6:7], s[18:19]
	s_mov_b64 s[14:15], s[52:53]
	s_waitcnt lgkmcnt(7)
	v_lshlrev_b32_e32 v180, 16, v180
	v_add_f32_e32 v0, v0, v180
	v_mul_f32_e32 v111, 0x3fb8aa3b, v0
	v_exp_f32_e32 v111, v111
	s_waitcnt lgkmcnt(6)
	v_lshlrev_b32_e32 v181, 16, v181
	v_mul_f32_e32 v180, 0x3fb8aa3b, v180
	v_exp_f32_e32 v180, v180
	v_mul_f32_e32 v181, v111, v181
	v_cvt_pk_bf16_f32 v181, v181, s0
	ds_write_b16 v108, v181 offset:576
	v_mul_f32_e32 v181, 0xbfb8aa3b, v0
	v_exp_f32_e32 v181, v181
	v_sub_f32_e32 v180, 1.0, v180
	s_mov_b64 s[36:37], s[2:3]
	s_mov_b64 s[20:21], s[12:13]
	v_mul_f32_e32 v180, v180, v181
	v_cvt_pk_bf16_f32 v180, v180, s0
	ds_write_b16 v108, v180 offset:19008
	s_mov_b64 s[92:93], s[38:39]
	s_mov_b64 s[22:23], s[40:41]
	s_waitcnt lgkmcnt(7)
	v_lshlrev_b32_e32 v182, 16, v182
	v_add_f32_e32 v0, v0, v182
	v_mul_f32_e32 v111, 0x3fb8aa3b, v0
	v_exp_f32_e32 v111, v111
	s_waitcnt lgkmcnt(6)
	v_lshlrev_b32_e32 v183, 16, v183
	v_mul_f32_e32 v182, 0x3fb8aa3b, v182
	v_exp_f32_e32 v182, v182
	v_mul_f32_e32 v183, v111, v183
	v_cvt_pk_bf16_f32 v183, v183, s0
	ds_write_b16 v108, v183 offset:864
	v_mul_f32_e32 v183, 0xbfb8aa3b, v0
	v_exp_f32_e32 v183, v183
	v_sub_f32_e32 v182, 1.0, v182
	v_mul_f32_e32 v182, v182, v183
	v_cvt_pk_bf16_f32 v182, v182, s0
	ds_write_b16 v108, v182 offset:19296
	s_cbranch_scc0 .LBB0_291
	s_branch .LBB0_278
